# GEMM phase prologues: K-tile 1 DMAs issued before waiting for K-tile 0 (vmcnt(2)->vmcnt(8) after the 6 loads)
# baseline (speedup 1.0000x reference)
.LBB0_25:
	v_readlane_b32 s13, v252, 28
	s_add_u32 s45, s13, 0x5000
	v_readlane_b32 s13, v252, 29
	s_addc_u32 s82, s13, 0
	s_add_i32 m0, s8, 0x18000
	v_lshl_add_u64 v[2:3], v[2:3], 0, s[60:61]
	global_load_lds_dwordx4 v[2:3], off
	v_lshl_add_u64 v[2:3], v[4:5], 0, s[60:61]
	s_add_i32 m0, s8, 0x1a000
	s_add_i32 s84, s8, 0x8000
	global_load_lds_dwordx4 v[2:3], off
	v_lshl_add_u64 v[2:3], v[10:11], 0, s[60:61]
	s_mov_b32 m0, s84
	s_add_i32 s96, s8, 0xa000
	global_load_lds_dwordx4 v[2:3], off
	v_lshl_add_u64 v[2:3], v[12:13], 0, s[60:61]
	s_mov_b32 m0, s96
	v_bfe_u32 v15, v14, 4, 2
	global_load_lds_dwordx4 v[2:3], off
	s_add_i32 m0, s8, 0x1c000
	v_lshl_add_u64 v[2:3], v[6:7], 0, s[60:61]
	global_load_lds_dwordx4 v[2:3], off
	v_lshl_add_u64 v[2:3], v[8:9], 0, s[60:61]
	s_add_i32 m0, s8, 0x1e000
	s_lshr_b32 s1, s1, 26
	global_load_lds_dwordx4 v[2:3], off
	s_waitcnt vmcnt(8)
	s_barrier
	v_and_b32_e32 v16, 15, v14
	s_add_i32 s1, s0, s1
	v_lshlrev_b32_e32 v17, 4, v15
	v_lshlrev_b32_e32 v14, 2, v14
	s_ashr_i32 s83, s1, 6
	v_lshl_or_b32 v1, s12, 6, v16
	v_lshl_or_b32 v16, v16, 6, v17
	s_lshl_b32 s1, s12, 13
	v_and_b32_e32 v14, 32, v14
	v_bitop3_b32 v17, v16, s1, v14 bitop3:0xde
	s_lshl_b32 s1, s3, 5
	s_and_b32 s3, s1, 0x60
	s_lshl_b32 s1, s3, 7
	s_cmp_gt_i32 s0, 63
	s_waitcnt vmcnt(6)
	s_cselect_b64 s[46:47], -1, 0
	s_add_i32 s97, s83, -2
	s_cmpk_lt_u32 s2, 0x100
	v_bitop3_b32 v169, v16, s1, v14 bitop3:0xde
	s_cselect_b64 s[0:1], -1, 0
	v_lshl_or_b32 v174, v15, 2, s3
	v_lshl_add_u64 v[150:151], s[14:15], 0, v[148:149]
	v_lshl_add_u64 v[152:153], s[14:15], 0, v[146:147]
	s_mov_b32 s98, 0
	v_add_u32_e32 v175, 0, v17
	v_readlane_b32 s43, v254, 49
	v_readlane_b32 s42, v254, 58
	s_barrier
	s_branch .LBB0_28

.LBB0_52:
	s_add_i32 m0, s8, 0x18000
	v_lshl_add_u64 v[2:3], v[2:3], 0, s[60:61]
	global_load_lds_dwordx4 v[2:3], off
	v_lshl_add_u64 v[2:3], v[4:5], 0, s[60:61]
	s_add_i32 m0, s8, 0x1a000
	s_add_i32 s82, s8, 0x8000
	global_load_lds_dwordx4 v[2:3], off
	v_lshl_add_u64 v[2:3], v[10:11], 0, s[60:61]
	s_mov_b32 m0, s82
	s_add_i32 s83, s8, 0xa000
	global_load_lds_dwordx4 v[2:3], off
	v_lshl_add_u64 v[2:3], v[12:13], 0, s[60:61]
	s_mov_b32 m0, s83
	v_lshrrev_b32_e32 v21, 1, v1
	global_load_lds_dwordx4 v[2:3], off
	s_add_i32 m0, s8, 0x1c000
	v_lshl_add_u64 v[2:3], v[6:7], 0, s[60:61]
	global_load_lds_dwordx4 v[2:3], off
	v_lshl_add_u64 v[2:3], v[8:9], 0, s[60:61]
	s_add_i32 m0, s8, 0x1e000
	s_lshr_b32 s28, s35, 26
	global_load_lds_dwordx4 v[2:3], off
	s_waitcnt vmcnt(8)
	s_barrier
	v_and_b32_e32 v21, 24, v21
	v_and_b32_e32 v20, 15, v1
	s_add_i32 s28, s34, s28
	v_lshlrev_b32_e32 v22, 1, v21
	v_lshlrev_b32_e32 v1, 2, v1
	s_ashr_i32 s45, s28, 6
	v_lshl_or_b32 v22, v20, 6, v22
	s_lshl_b32 s28, s3, 13
	v_and_b32_e32 v1, 32, v1
	v_bitop3_b32 v23, v22, s28, v1 bitop3:0xde
	s_lshl_b32 s28, s36, 5
	s_and_b32 s28, s28, 0x60
	v_lshlrev_b32_e32 v2, 13, v20
	s_lshl_b32 s35, s28, 7
	v_lshl_or_b32 v142, s3, 19, v2
	v_add_u32_e32 v2, v19, v17
	s_cmp_gt_i32 s34, 63
	v_add_lshl_u32 v2, v2, v18, 1
	v_mov_b32_e32 v3, v0
	v_bitop3_b32 v1, v22, s35, v1 bitop3:0xde
	s_waitcnt vmcnt(6)
	s_cselect_b64 s[34:35], -1, 0
	s_add_i32 s84, s45, -2
	v_lshl_add_u64 v[138:139], s[0:1], 0, v[2:3]
	v_add_u32_e32 v2, v16, v14
	s_cmpk_lt_u32 s2, 0x100
	v_or_b32_e32 v4, s28, v21
	v_add_lshl_u32 v2, v2, v15, 1
	s_cselect_b64 s[42:43], -1, 0
	v_lshl_add_u64 v[140:141], s[0:1], 0, v[2:3]
	s_mov_b32 s96, 0
	v_add_u32_e32 v143, 0, v23
	v_lshlrev_b32_e32 v144, 1, v4
	v_readlane_b32 s99, v254, 52
	v_readlane_b32 s98, v254, 60
	s_barrier
	s_branch .LBB0_55

.LBB0_87:
	v_readlane_b32 s13, v252, 28
	s_add_u32 s45, s13, 0x2000
	v_readlane_b32 s13, v252, 29
	s_addc_u32 s82, s13, 0
	s_add_i32 m0, s8, 0x18000
	v_lshl_add_u64 v[2:3], v[2:3], 0, s[60:61]
	global_load_lds_dwordx4 v[2:3], off
	v_lshl_add_u64 v[2:3], v[4:5], 0, s[60:61]
	s_add_i32 m0, s8, 0x1a000
	s_add_i32 s84, s8, 0x8000
	global_load_lds_dwordx4 v[2:3], off
	v_lshl_add_u64 v[2:3], v[10:11], 0, s[60:61]
	s_mov_b32 m0, s84
	s_add_i32 s96, s8, 0xa000
	global_load_lds_dwordx4 v[2:3], off
	v_lshl_add_u64 v[2:3], v[12:13], 0, s[60:61]
	s_mov_b32 m0, s96
	v_bfe_u32 v15, v14, 4, 2
	global_load_lds_dwordx4 v[2:3], off
	s_add_i32 m0, s8, 0x1c000
	v_lshl_add_u64 v[2:3], v[6:7], 0, s[60:61]
	global_load_lds_dwordx4 v[2:3], off
	v_lshl_add_u64 v[2:3], v[8:9], 0, s[60:61]
	s_add_i32 m0, s8, 0x1e000
	v_and_b32_e32 v16, 15, v14
	global_load_lds_dwordx4 v[2:3], off
	s_waitcnt vmcnt(8)
	s_barrier
	s_lshr_b32 s13, s35, 26
	v_lshlrev_b32_e32 v17, 4, v15
	v_lshlrev_b32_e32 v14, 2, v14
	s_lshl_b32 s3, s3, 5
	s_add_i32 s13, s34, s13
	v_lshl_or_b32 v1, s12, 6, v16
	v_lshl_or_b32 v16, v16, 6, v17
	s_lshl_b32 s12, s12, 13
	v_and_b32_e32 v14, 32, v14
	s_and_b32 s3, s3, 0x60
	s_ashr_i32 s83, s13, 6
	v_bitop3_b32 v17, v16, s12, v14 bitop3:0xde
	s_lshl_b32 s12, s3, 7
	s_cmp_gt_i32 s34, 63
	s_waitcnt vmcnt(6)
	s_cselect_b64 s[34:35], -1, 0
	s_add_i32 s97, s83, -2
	s_cmpk_lt_u32 s2, 0x100
	v_bitop3_b32 v169, v16, s12, v14 bitop3:0xde
	s_cselect_b64 s[42:43], -1, 0
	v_lshl_or_b32 v174, v15, 2, s3
	v_lshl_add_u64 v[150:151], s[0:1], 0, v[148:149]
	v_lshl_add_u64 v[152:153], s[0:1], 0, v[146:147]
	s_mov_b32 s98, 0
	v_add_u32_e32 v175, 0, v17
	v_readlane_b32 s99, v254, 49
	v_readlane_b32 s2, v254, 58
	s_barrier
	s_branch .LBB0_90

.LBB0_116:
	v_mov_b32_e32 v175, v0
	v_lshl_add_u64 v[8:9], s[12:13], 0, v[174:175]
	v_mov_b32_e32 v171, v0
	v_lshl_add_u64 v[10:11], s[12:13], 0, v[170:171]
	v_mov_b32_e32 v177, v0
	s_add_i32 m0, s8, 0x18000
	v_lshl_add_u64 v[8:9], v[8:9], 0, s[60:61]
	v_lshl_add_u64 v[16:17], s[0:1], 0, v[176:177]
	v_mov_b32_e32 v173, v0
	global_load_lds_dwordx4 v[8:9], off
	v_lshl_add_u64 v[8:9], v[10:11], 0, s[60:61]
	s_add_i32 m0, s8, 0x1a000
	s_add_i32 s84, s8, 0x8000
	v_lshl_add_u64 v[18:19], s[0:1], 0, v[172:173]
	global_load_lds_dwordx4 v[8:9], off
	v_lshl_add_u64 v[8:9], v[16:17], 0, s[60:61]
	s_mov_b32 m0, s84
	s_add_i32 s29, s8, 0xa000
	v_lshl_add_u64 v[12:13], s[36:37], 0, v[174:175]
	global_load_lds_dwordx4 v[8:9], off
	v_lshl_add_u64 v[8:9], v[18:19], 0, s[60:61]
	s_mov_b32 m0, s29
	v_lshl_add_u64 v[14:15], s[36:37], 0, v[170:171]
	global_load_lds_dwordx4 v[8:9], off
	s_add_i32 m0, s8, 0x1c000
	v_lshl_add_u64 v[8:9], v[12:13], 0, s[60:61]
	global_load_lds_dwordx4 v[8:9], off
	v_lshl_add_u64 v[8:9], v[14:15], 0, s[60:61]
	s_add_i32 m0, s8, 0x1e000
	v_bfe_u32 v169, v7, 4, 2
	global_load_lds_dwordx4 v[8:9], off
	s_waitcnt vmcnt(8)
	s_barrier
	v_and_b32_e32 v192, 15, v7
	v_lshlrev_b32_e32 v20, 4, v169
	v_lshlrev_b32_e32 v7, 2, v7
	s_lshr_b32 s2, s21, 26
	v_lshl_or_b32 v20, v192, 6, v20
	s_lshl_b32 s21, s28, 13
	v_and_b32_e32 v7, 32, v7
	v_bitop3_b32 v21, v20, s21, v7 bitop3:0xde
	s_lshl_b32 s21, s26, 5
	s_add_i32 s2, s20, s2
	s_and_b32 s83, s21, 0x60
	s_ashr_i32 s2, s2, 6
	s_lshl_b32 s82, s28, 6
	s_lshl_b32 s21, s83, 7
	s_cmp_gt_i32 s20, 63
	v_bitop3_b32 v193, v20, s21, v7 bitop3:0xde
	s_waitcnt vmcnt(6)
	s_cselect_b64 s[20:21], -1, 0
	s_add_i32 s81, s2, -2
	v_add_u32_e32 v4, v6, v4
	v_add_u32_e32 v1, v3, v1
	s_cmpk_lt_u32 s3, 0x100
	v_add_lshl_u32 v4, v4, v5, 1
	v_mov_b32_e32 v5, v0
	v_add_lshl_u32 v2, v1, v2, 1
	v_mov_b32_e32 v3, v0
	v_writelane_b32 v252, s20, 38
	s_cselect_b64 s[46:47], -1, 0
	v_lshl_add_u64 v[178:179], s[14:15], 0, v[4:5]
	v_lshl_add_u64 v[180:181], s[14:15], 0, v[2:3]
	s_mov_b32 s3, 0
	v_add_u32_e32 v194, 0, v21
	v_readlane_b32 s97, v254, 49
	v_readlane_b32 s98, v254, 58
	s_barrier
	v_writelane_b32 v252, s21, 39
	s_branch .LBB0_119

.LBB0_257:
	v_readlane_b32 s9, v252, 31
	s_lshl_b32 s8, s9, 13
	s_add_u32 s20, s76, s8
	s_addc_u32 s21, s77, 0
	s_add_i32 m0, s80, 0x18000
	v_lshl_add_u64 v[10:11], v[10:11], 0, s[60:61]
	global_load_lds_dwordx4 v[10:11], off
	v_lshl_add_u64 v[6:7], v[6:7], 0, s[60:61]
	s_add_i32 m0, s80, 0x1a000
	s_add_i32 s42, s80, 0x8000
	global_load_lds_dwordx4 v[6:7], off
	v_lshl_add_u64 v[6:7], v[8:9], 0, s[60:61]
	s_mov_b32 m0, s42
	s_add_i32 s43, s80, 0xa000
	global_load_lds_dwordx4 v[6:7], off
	v_lshl_add_u64 v[6:7], v[12:13], 0, s[60:61]
	s_mov_b32 m0, s43
	v_lshl_add_u64 v[4:5], v[4:5], 0, s[60:61]
	global_load_lds_dwordx4 v[6:7], off
	s_add_i32 m0, s80, 0x1c000
	v_lshl_add_u64 v[2:3], v[2:3], 0, s[60:61]
	global_load_lds_dwordx4 v[4:5], off
	s_add_i32 m0, s80, 0x1e000
	s_mul_i32 s8, s9, 0x500
	global_load_lds_dwordx4 v[2:3], off
	s_waitcnt vmcnt(8)
	s_barrier
	v_lshrrev_b32_e32 v2, 1, v14
	v_and_b32_e32 v154, 24, v2
	v_and_b32_e32 v1, 15, v14
	s_and_b32 s9, s4, 3
	s_lshr_b32 s4, s15, 26
	v_lshlrev_b32_e32 v2, 1, v154
	v_lshlrev_b32_e32 v3, 2, v14
	s_add_i32 s4, s14, s4
	v_lshl_or_b32 v155, s3, 6, v1
	v_lshl_or_b32 v2, v1, 6, v2
	s_lshl_b32 s3, s3, 13
	v_and_b32_e32 v3, 32, v3
	s_ashr_i32 s84, s4, 6
	v_bitop3_b32 v4, v2, s3, v3 bitop3:0xde
	s_lshl_b32 s3, s9, 12
	s_cmp_gt_i32 s14, 63
	s_cselect_b64 s[48:49], -1, 0
	s_add_i32 s45, s84, -2
	v_bitop3_b32 v169, v2, s3, v3 bitop3:0xde
	s_cmpk_lt_u32 s2, 0x100
	v_lshl_or_b32 v2, s9, 5, v154
	s_cselect_b64 s[50:51], -1, 0
	v_or_b32_e32 v190, 0xfffff880, v2
	s_add_u32 s2, s20, 0x1000
	v_writelane_b32 v252, s20, 29
	v_add_u32_e32 v2, v20, v18
	s_addc_u32 s3, s21, 0
	v_writelane_b32 v252, s21, 30
	v_add_lshl_u32 v2, v2, v19, 1
	v_mov_b32_e32 v3, v0
	s_waitcnt vmcnt(6)
	v_writelane_b32 v252, s2, 38
	v_lshl_add_u64 v[170:171], s[30:31], 0, v[2:3]
	v_add_u32_e32 v2, v17, v15
	v_writelane_b32 v252, s3, 39
	v_add_lshl_u32 v2, v2, v16, 1
	s_lshl_b32 s3, s8, 2
	s_mov_b32 s44, s9
	v_lshl_or_b32 v191, s9, 6, v154
	v_lshl_add_u64 v[172:173], s[30:31], 0, v[2:3]
	s_mov_b32 s2, 0
	v_add_u32_e32 v192, 0, v4
	v_writelane_b32 v252, s3, 28
	v_readlane_b32 s83, v254, 55
	v_readlane_b32 s3, v254, 62
	s_barrier
	s_branch .LBB0_260
